# rownorm wave sums: ds_bpermute butterfly replaced by permlane32/16 swap + DPP adds (same butterfly order, bitwise identical)
# speedup vs baseline: 1.0023x; 1.0023x over previous
; DI unsigned pack2(float lo, float hi) { f32x2 v = {lo, hi}; bf2_t b = __builtin_convertvector(v, bf2_t); return __builtin_bit_cast(unsigned, b); }
; DI float wave_sum(float v) { v += __shfl_xor(v, 32); v += __shfl_xor(v, 16); v += __shfl_xor(v, 8); v += __shfl_xor(v, 4); v += __shfl_xor(v, 2); v += __shfl_xor(v, 1); return v; }
; DI void rownorm_phase(const Params& P, const float* xin, const bf16_t* yin, float* xout, bf16_t* hout, int lg, int gate_idx, const float* w_post,
;                       int lh, int scale_idx, int shift_idx, const float* w_pre, char* smem) {
;     ...
;     if (hout) {
;       float ss = 0.f;
; #pragma unroll
;       for (int j = 0; j < 8; ++j) ss += xv[j].x * xv[j].x + xv[j].y * xv[j].y + xv[j].z * xv[j].z + xv[j].w * xv[j].w;
;       ss = wave_sum(ss); const float r = rsqrtf(ss * (1.f / 2048.f) + EPS);
; #pragma unroll
;       for (int j = 0; j < 8; ++j) { const f32x4 a = *(const f32x4*)(A2 + (j * 64 + lane) * 4), b = *(const f32x4*)(B2 + (j * 64 + lane) * 4);
;         const f32x4 hv = xv[j] * r * a + b; u32x2 pk = {pack2(hv.x, hv.y), pack2(hv.z, hv.w)};
;         *(u32x2*)(hout + (size_t)row * 2048 + (j * 64 + lane) * 4) = pk; }
;     }
.LBB0_109:
	s_waitcnt vmcnt(0) lgkmcnt(0)
	v_mul_f32_e32 v50, v29, v29
	v_mul_f32_e32 v51, v25, v25
	v_fmac_f32_e32 v50, v28, v28
	v_fmac_f32_e32 v51, v24, v24
	v_fmac_f32_e32 v50, v30, v30
	v_fmac_f32_e32 v51, v26, v26
	v_fmac_f32_e32 v50, v31, v31
	v_fmac_f32_e32 v51, v27, v27
	v_add_f32_e32 v50, v50, v51
	v_mul_f32_e32 v51, v21, v21
	v_fmac_f32_e32 v51, v20, v20
	v_fmac_f32_e32 v51, v22, v22
	v_fmac_f32_e32 v51, v23, v23
	v_add_f32_e32 v50, v50, v51
	v_mul_f32_e32 v51, v17, v17
	v_fmac_f32_e32 v51, v16, v16
	v_fmac_f32_e32 v51, v18, v18
	v_fmac_f32_e32 v51, v19, v19
	v_mov_b32_e32 v60, v13
	v_mov_b32_e32 v61, v9
	v_add_f32_e32 v62, v50, v51
	v_mov_b32_e32 v50, v12
	v_mov_b32_e32 v51, v8
	v_pk_mul_f32 v[60:61], v[60:61], v[60:61]
	v_lshlrev_b64 v[72:73], 12, v[36:37]
	v_pk_fma_f32 v[50:51], v[50:51], v[50:51], v[60:61]
	v_mov_b32_e32 v60, v14
	v_mov_b32_e32 v61, v10
	v_pk_fma_f32 v[50:51], v[60:61], v[60:61], v[50:51]
	v_mov_b32_e32 v60, v15
	v_mov_b32_e32 v61, v11
	v_pk_fma_f32 v[50:51], v[60:61], v[60:61], v[50:51]
	v_mov_b32_e32 v60, v5
	v_add_f32_e32 v50, v62, v50
	v_mov_b32_e32 v61, v1
	v_add_f32_e32 v62, v50, v51
	v_mov_b32_e32 v50, v4
	v_mov_b32_e32 v51, v0
	v_pk_mul_f32 v[60:61], v[60:61], v[60:61]
	v_add_u32_e32 v36, s6, v36
	v_pk_fma_f32 v[50:51], v[50:51], v[50:51], v[60:61]
	v_mov_b32_e32 v60, v6
	v_mov_b32_e32 v61, v2
	v_pk_fma_f32 v[50:51], v[60:61], v[60:61], v[50:51]
	v_mov_b32_e32 v60, v7
	v_mov_b32_e32 v61, v3
	v_pk_fma_f32 v[50:51], v[60:61], v[60:61], v[50:51]
	s_nop 0
	v_add_f32_e32 v50, v62, v50
	v_add_f32_e32 v50, v50, v51
	v_mov_b32_e32 v120, v50
	v_mov_b32_e32 v121, v50
	s_nop 1
	v_permlane32_swap_b32_e32 v120, v121
	ds_read_b128 v[60:63], v52 offset:8192
	ds_read_b128 v[64:67], v52 offset:16384
	s_waitcnt lgkmcnt(2)
	v_add_f32_e32 v50, v120, v121
	v_mov_b32_e32 v120, v50
	v_mov_b32_e32 v121, v50
	s_nop 1
	v_permlane16_swap_b32_e32 v120, v121
	s_waitcnt lgkmcnt(0)
	v_add_f32_e32 v50, v120, v121
	s_nop 1
	s_waitcnt lgkmcnt(0)
	v_add_f32_dpp v50, v50, v50 row_ror:8 row_mask:0xf bank_mask:0xf
	s_nop 1
	v_mov_b32_dpp v120, v50 row_ror:4 row_mask:0xf bank_mask:0xa
	v_mov_b32_dpp v120, v50 row_ror:12 row_mask:0xf bank_mask:0x5
	s_waitcnt lgkmcnt(0)
	v_add_f32_e32 v50, v50, v120
	s_nop 1
	s_waitcnt lgkmcnt(0)
	v_add_f32_dpp v50, v50, v50 quad_perm:[2,3,0,1] row_mask:0xf bank_mask:0xf
	s_nop 1
	s_waitcnt lgkmcnt(0)
	v_add_f32_dpp v50, v50, v50 quad_perm:[1,0,3,2] row_mask:0xf bank_mask:0xf
	v_fmamk_f32 v50, v50, 0x3a000000, v59
	v_mul_f32_e32 v51, 0x4b800000, v50
	v_cmp_gt_f32_e32 vcc, s7, v50
	s_nop 1
	v_cndmask_b32_e32 v50, v50, v51, vcc
	v_rsq_f32_e32 v50, v50
	s_nop 0
	v_mul_f32_e32 v51, 0x45800000, v50
	v_cndmask_b32_e32 v50, v50, v51, vcc
	v_pk_mul_f32 v[74:75], v[28:29], v[50:51] op_sel_hi:[1,0]
	v_pk_mul_f32 v[76:77], v[30:31], v[50:51] op_sel_hi:[1,0]
	ds_read_b128 v[28:31], v52 offset:9216
	ds_read_b128 v[68:71], v52 offset:17408
	v_pk_mul_f32 v[24:25], v[24:25], v[50:51] op_sel_hi:[1,0]
	v_pk_mul_f32 v[26:27], v[26:27], v[50:51] op_sel_hi:[1,0]
	v_pk_fma_f32 v[62:63], v[62:63], v[76:77], v[66:67]
	v_pk_fma_f32 v[60:61], v[60:61], v[74:75], v[64:65]
	s_waitcnt lgkmcnt(0)
	v_pk_fma_f32 v[26:27], v[30:31], v[26:27], v[70:71]
	v_pk_fma_f32 v[24:25], v[28:29], v[24:25], v[68:69]
	v_cvt_pk_bf16_f32 v60, v60, v61
	v_cvt_pk_bf16_f32 v61, v62, v63
	v_lshl_add_u64 v[64:65], v[40:41], 0, v[72:73]
	v_cvt_pk_bf16_f32 v24, v24, v25
	v_cvt_pk_bf16_f32 v25, v26, v27
	global_store_dwordx2 v[64:65], v[60:61], off
	global_store_dwordx2 v[64:65], v[24:25], off offset:512
	ds_read_b128 v[24:27], v52 offset:10240
	ds_read_b128 v[28:31], v52 offset:18432
	v_pk_mul_f32 v[66:67], v[20:21], v[50:51] op_sel_hi:[1,0]
	v_pk_mul_f32 v[68:69], v[22:23], v[50:51] op_sel_hi:[1,0]
	ds_read_b128 v[20:23], v52 offset:11264
	ds_read_b128 v[60:63], v52 offset:19456
	v_pk_mul_f32 v[16:17], v[16:17], v[50:51] op_sel_hi:[1,0]
	v_pk_mul_f32 v[18:19], v[18:19], v[50:51] op_sel_hi:[1,0]
	s_waitcnt lgkmcnt(2)
	v_pk_fma_f32 v[26:27], v[26:27], v[68:69], v[30:31]
	v_pk_fma_f32 v[24:25], v[24:25], v[66:67], v[28:29]
	s_waitcnt lgkmcnt(0)
	v_pk_fma_f32 v[18:19], v[22:23], v[18:19], v[62:63]
	v_pk_fma_f32 v[16:17], v[20:21], v[16:17], v[60:61]
	v_cvt_pk_bf16_f32 v24, v24, v25
	v_cvt_pk_bf16_f32 v25, v26, v27
	v_cvt_pk_bf16_f32 v16, v16, v17
	v_cvt_pk_bf16_f32 v17, v18, v19
	global_store_dwordx2 v[64:65], v[24:25], off offset:1024
	global_store_dwordx2 v[64:65], v[16:17], off offset:1536
	ds_read_b128 v[16:19], v52 offset:12288
	ds_read_b128 v[20:23], v52 offset:20480
	v_pk_mul_f32 v[28:29], v[12:13], v[50:51] op_sel_hi:[1,0]
	v_pk_mul_f32 v[30:31], v[14:15], v[50:51] op_sel_hi:[1,0]
	ds_read_b128 v[12:15], v52 offset:13312
	ds_read_b128 v[24:27], v52 offset:21504
	v_pk_mul_f32 v[8:9], v[8:9], v[50:51] op_sel_hi:[1,0]
	v_pk_mul_f32 v[10:11], v[10:11], v[50:51] op_sel_hi:[1,0]
	s_waitcnt lgkmcnt(2)
	v_pk_fma_f32 v[18:19], v[30:31], v[18:19], v[22:23]
	v_pk_fma_f32 v[16:17], v[28:29], v[16:17], v[20:21]
	s_waitcnt lgkmcnt(0)
	v_pk_fma_f32 v[10:11], v[10:11], v[14:15], v[26:27]
	v_pk_fma_f32 v[8:9], v[8:9], v[12:13], v[24:25]
	v_cvt_pk_bf16_f32 v16, v16, v17
	v_cvt_pk_bf16_f32 v17, v18, v19
	v_cvt_pk_bf16_f32 v8, v8, v9
	v_cvt_pk_bf16_f32 v9, v10, v11
	global_store_dwordx2 v[64:65], v[16:17], off offset:2048
	global_store_dwordx2 v[64:65], v[8:9], off offset:2560
	ds_read_b128 v[8:11], v52 offset:14336
	ds_read_b128 v[12:15], v52 offset:22528
	v_pk_mul_f32 v[20:21], v[4:5], v[50:51] op_sel_hi:[1,0]
	v_pk_mul_f32 v[22:23], v[6:7], v[50:51] op_sel_hi:[1,0]
	ds_read_b128 v[4:7], v52 offset:15360
	ds_read_b128 v[16:19], v52 offset:23552
	v_pk_mul_f32 v[0:1], v[0:1], v[50:51] op_sel_hi:[1,0]
	v_pk_mul_f32 v[2:3], v[2:3], v[50:51] op_sel_hi:[1,0]
	s_waitcnt lgkmcnt(2)
	v_pk_fma_f32 v[10:11], v[22:23], v[10:11], v[14:15]
	v_pk_fma_f32 v[8:9], v[20:21], v[8:9], v[12:13]
	s_waitcnt lgkmcnt(0)
	v_pk_fma_f32 v[2:3], v[2:3], v[6:7], v[18:19]
	v_pk_fma_f32 v[0:1], v[0:1], v[4:5], v[16:17]
	v_cmp_lt_i32_e32 vcc, s8, v36
	v_cvt_pk_bf16_f32 v8, v8, v9
	v_cvt_pk_bf16_f32 v9, v10, v11
	v_cvt_pk_bf16_f32 v0, v0, v1
	v_cvt_pk_bf16_f32 v1, v2, v3
	s_or_b64 s[4:5], vcc, s[4:5]
	global_store_dwordx2 v[64:65], v[8:9], off offset:3072
	global_store_dwordx2 v[64:65], v[0:1], off offset:3584
	s_andn2_b64 exec, exec, s[4:5]
	s_cbranch_execz .LBB0_112

; DI float bflo(unsigned u) { return __uint_as_float(u << 16); }
; DI float bfhi(unsigned u) { return __uint_as_float(u & 0xffff0000u); }
; DI float wave_sum(float v) { v += __shfl_xor(v, 32); v += __shfl_xor(v, 16); v += __shfl_xor(v, 8); v += __shfl_xor(v, 4); v += __shfl_xor(v, 2); v += __shfl_xor(v, 1); return v; }
; DI void rownorm_phase(const Params& P, const float* xin, const bf16_t* yin, float* xout, bf16_t* hout, int lg, int gate_idx, const float* w_post,
;                       int lh, int scale_idx, int shift_idx, const float* w_pre, char* smem) {
;     ...
;     f32x4 xv[8];
; #pragma unroll
;     for (int j = 0; j < 8; ++j) xv[j] = __builtin_nontemporal_load((const f32x4*)(xin + (size_t)row * 2048 + (j * 64 + lane) * 4));
;     if (yin) {
;       f32x4 yv[8]; float ss = 0.f;
; #pragma unroll
;       for (int j = 0; j < 8; ++j) { const u32x2 yb = __builtin_nontemporal_load((const u32x2*)(yin + (size_t)row * 2048 + (j * 64 + lane) * 4)); yv[j] = (f32x4){bflo(yb.x), bfhi(yb.x), bflo(yb.y), bfhi(yb.y)};
;         ss += yv[j].x * yv[j].x + yv[j].y * yv[j].y + yv[j].z * yv[j].z + yv[j].w * yv[j].w; }
;       ss = wave_sum(ss); const float r = rsqrtf(ss * (1.f / 2048.f) + EPS);
; #pragma unroll
;       for (int j = 0; j < 8; ++j) { const f32x4 a = *(const f32x4*)(A1 + (j * 64 + lane) * 4); xv[j] += a * (yv[j] * r); }
.LBB0_889:
	v_ashrrev_i32_e32 v37, 31, v36
	v_lshlrev_b64 v[2:3], 13, v[36:37]
	v_lshl_add_u64 v[2:3], v[34:35], 0, v[2:3]
	v_lshlrev_b64 v[50:51], 12, v[36:37]
	v_lshl_add_u64 v[52:53], v[2:3], 0, v[0:1]
	v_lshl_add_u64 v[86:87], v[38:39], 0, v[50:51]
	global_load_dwordx4 v[30:33], v[52:53], off nt
	global_load_dwordx4 v[26:29], v[52:53], off offset:1024 nt
	global_load_dwordx4 v[22:25], v[52:53], off offset:2048 nt
	global_load_dwordx4 v[18:21], v[52:53], off offset:3072 nt
	global_load_dwordx2 v[62:63], v[86:87], off nt
	v_mov_b32_e32 v43, v1
	v_mov_b32_e32 v45, v1
	v_mov_b32_e32 v47, v1
	v_mov_b32_e32 v49, v1
	v_lshl_add_u64 v[54:55], v[2:3], 0, v[42:43]
	v_lshl_add_u64 v[56:57], v[2:3], 0, v[44:45]
	v_lshl_add_u64 v[58:59], v[2:3], 0, v[46:47]
	v_lshl_add_u64 v[60:61], v[2:3], 0, v[48:49]
	global_load_dwordx4 v[14:17], v[54:55], off nt
	global_load_dwordx4 v[10:13], v[56:57], off nt
	global_load_dwordx4 v[6:9], v[58:59], off nt
	global_load_dwordx4 v[2:5], v[60:61], off nt
	global_load_dwordx2 v[106:107], v[86:87], off offset:512 nt
	global_load_dwordx2 v[108:109], v[86:87], off offset:1024 nt
	global_load_dwordx2 v[110:111], v[86:87], off offset:1536 nt
	global_load_dwordx2 v[88:89], v[86:87], off offset:2048 nt
	global_load_dwordx2 v[66:67], v[86:87], off offset:2560 nt
	global_load_dwordx2 v[102:103], v[86:87], off offset:3072 nt
	global_load_dwordx2 v[92:93], v[86:87], off offset:3584 nt
	s_waitcnt vmcnt(11)
	v_add_u32_e32 v36, s79, v36
	v_lshlrev_b32_e32 v70, 16, v62
	v_and_b32_e32 v71, 0xffff0000, v62
	v_lshlrev_b32_e32 v72, 16, v63
	v_and_b32_e32 v73, 0xffff0000, v63
	v_mul_f32_e32 v37, v71, v71
	v_fmac_f32_e32 v37, v70, v70
	v_fmac_f32_e32 v37, v72, v72
	v_fmac_f32_e32 v37, v73, v73
	s_waitcnt vmcnt(6)
	v_lshlrev_b32_e32 v74, 16, v106
	v_and_b32_e32 v75, 0xffff0000, v106
	v_lshlrev_b32_e32 v76, 16, v107
	v_and_b32_e32 v77, 0xffff0000, v107
	v_mul_f32_e32 v43, v75, v75
	v_fmac_f32_e32 v43, v74, v74
	v_fmac_f32_e32 v43, v76, v76
	v_fmac_f32_e32 v43, v77, v77
	v_add_f32_e32 v37, v37, v43
	s_waitcnt vmcnt(5)
	v_lshlrev_b32_e32 v78, 16, v108
	v_and_b32_e32 v79, 0xffff0000, v108
	v_lshlrev_b32_e32 v80, 16, v109
	v_and_b32_e32 v81, 0xffff0000, v109
	v_mul_f32_e32 v43, v79, v79
	v_fmac_f32_e32 v43, v78, v78
	v_fmac_f32_e32 v43, v80, v80
	v_fmac_f32_e32 v43, v81, v81
	v_add_f32_e32 v37, v37, v43
	s_waitcnt vmcnt(0)
	v_lshlrev_b32_e32 v64, 16, v88
	v_and_b32_e32 v83, 0xffff0000, v110
	v_lshlrev_b32_e32 v82, 16, v110
	v_lshlrev_b32_e32 v84, 16, v111
	v_and_b32_e32 v85, 0xffff0000, v111
	v_mul_f32_e32 v43, v83, v83
	v_and_b32_e32 v63, 0xffff0000, v66
	v_and_b32_e32 v62, 0xffff0000, v88
	v_fmac_f32_e32 v43, v82, v82
	v_lshlrev_b32_e32 v65, 16, v66
	v_lshlrev_b32_e32 v68, 16, v89
	v_and_b32_e32 v66, 0xffff0000, v89
	v_pk_mul_f32 v[88:89], v[62:63], v[62:63]
	v_fmac_f32_e32 v43, v84, v84
	v_lshlrev_b32_e32 v69, 16, v67
	v_pk_fma_f32 v[88:89], v[64:65], v[64:65], v[88:89]
	v_fmac_f32_e32 v43, v85, v85
	v_and_b32_e32 v67, 0xffff0000, v67
	v_pk_fma_f32 v[88:89], v[68:69], v[68:69], v[88:89]
	v_add_f32_e32 v37, v37, v43
	v_pk_fma_f32 v[88:89], v[66:67], v[66:67], v[88:89]
	v_lshlrev_b32_e32 v87, 16, v92
	v_add_f32_e32 v37, v37, v88
	v_add_f32_e32 v37, v37, v89
	v_and_b32_e32 v89, 0xffff0000, v92
	v_and_b32_e32 v88, 0xffff0000, v102
	v_lshlrev_b32_e32 v86, 16, v102
	v_lshlrev_b32_e32 v90, 16, v103
	v_and_b32_e32 v92, 0xffff0000, v103
	v_pk_mul_f32 v[102:103], v[88:89], v[88:89]
	v_lshlrev_b32_e32 v91, 16, v93
	v_pk_fma_f32 v[102:103], v[86:87], v[86:87], v[102:103]
	v_and_b32_e32 v93, 0xffff0000, v93
	v_pk_fma_f32 v[102:103], v[90:91], v[90:91], v[102:103]
	s_nop 0
	v_pk_fma_f32 v[102:103], v[92:93], v[92:93], v[102:103]
	s_nop 0
	v_add_f32_e32 v37, v37, v102
	v_add_f32_e32 v37, v37, v103
	v_mov_b32_e32 v120, v37
	v_mov_b32_e32 v121, v37
	s_nop 1
	v_permlane32_swap_b32_e32 v120, v121
	ds_read_b128 v[102:105], v95
	s_waitcnt lgkmcnt(0)
	v_add_f32_e32 v37, v120, v121
	v_mov_b32_e32 v120, v37
	v_mov_b32_e32 v121, v37
	s_nop 1
	v_permlane16_swap_b32_e32 v120, v121
	s_waitcnt lgkmcnt(0)
	v_add_f32_e32 v37, v120, v121
	s_nop 1
	s_waitcnt lgkmcnt(0)
	v_add_f32_dpp v37, v37, v37 row_ror:8 row_mask:0xf bank_mask:0xf
	s_nop 1
	v_mov_b32_dpp v120, v37 row_ror:4 row_mask:0xf bank_mask:0xa
	v_mov_b32_dpp v120, v37 row_ror:12 row_mask:0xf bank_mask:0x5
	s_waitcnt lgkmcnt(0)
	v_add_f32_e32 v37, v37, v120
	s_nop 1
	s_waitcnt lgkmcnt(0)
	v_add_f32_dpp v37, v37, v37 quad_perm:[2,3,0,1] row_mask:0xf bank_mask:0xf
	s_nop 1
	s_waitcnt lgkmcnt(0)
	v_add_f32_dpp v37, v37, v37 quad_perm:[1,0,3,2] row_mask:0xf bank_mask:0xf
	v_fmamk_f32 v37, v37, 0x3a000000, v245
	v_cmp_gt_f32_e32 vcc, s84, v37
	v_mul_f32_e32 v43, 0x4b800000, v37
	s_nop 0
	v_cndmask_b32_e32 v37, v37, v43, vcc
	v_rsq_f32_e32 v37, v37
	s_nop 0
	v_mul_f32_e32 v43, 0x45800000, v37
	v_cndmask_b32_e32 v94, v37, v43, vcc
	v_pk_mul_f32 v[70:71], v[70:71], v[94:95] op_sel_hi:[1,0]
	v_pk_mul_f32 v[72:73], v[72:73], v[94:95] op_sel_hi:[1,0]
	v_pk_fma_f32 v[30:31], v[102:103], v[70:71], v[30:31]
	v_pk_fma_f32 v[32:33], v[104:105], v[72:73], v[32:33]
	ds_read_b128 v[70:73], v95 offset:1024
	v_pk_mul_f32 v[74:75], v[74:75], v[94:95] op_sel_hi:[1,0]
	v_pk_mul_f32 v[76:77], v[76:77], v[94:95] op_sel_hi:[1,0]
	v_mul_f32_e32 v37, v31, v31
	v_fmac_f32_e32 v37, v30, v30
	s_waitcnt lgkmcnt(0)
	v_pk_fma_f32 v[28:29], v[72:73], v[76:77], v[28:29]
	v_pk_fma_f32 v[26:27], v[70:71], v[74:75], v[26:27]
	ds_read_b128 v[70:73], v95 offset:2048
	v_pk_mul_f32 v[74:75], v[78:79], v[94:95] op_sel_hi:[1,0]
	v_pk_mul_f32 v[76:77], v[80:81], v[94:95] op_sel_hi:[1,0]
	v_mul_f32_e32 v43, v27, v27
	v_fmac_f32_e32 v43, v26, v26
	s_waitcnt lgkmcnt(0)
; DI float wave_sum(float v) { v += __shfl_xor(v, 32); v += __shfl_xor(v, 16); v += __shfl_xor(v, 8); v += __shfl_xor(v, 4); v += __shfl_xor(v, 2); v += __shfl_xor(v, 1); return v; }
; DI void rownorm_phase(const Params& P, const float* xin, const bf16_t* yin, float* xout, bf16_t* hout, int lg, int gate_idx, const float* w_post,
;                       int lh, int scale_idx, int shift_idx, const float* w_pre, char* smem) {
;     ...
;       for (int j = 0; j < 8; ++j) { const f32x4 a = *(const f32x4*)(A1 + (j * 64 + lane) * 4); xv[j] += a * (yv[j] * r); }
;     }
;     if (yin || xout != xin) {
; #pragma unroll
;       for (int j = 0; j < 8; ++j) __builtin_nontemporal_store(xv[j], (f32x4*)(xout + (size_t)row * 2048 + (j * 64 + lane) * 4));
;     }
;     if (hout) {
;       float ss = 0.f;
; #pragma unroll
;       for (int j = 0; j < 8; ++j) ss += xv[j].x * xv[j].x + xv[j].y * xv[j].y + xv[j].z * xv[j].z + xv[j].w * xv[j].w;
;       ss = wave_sum(ss); const float r = rsqrtf(ss * (1.f / 2048.f) + EPS);
	v_pk_fma_f32 v[24:25], v[72:73], v[76:77], v[24:25]
	v_pk_fma_f32 v[22:23], v[70:71], v[74:75], v[22:23]
	ds_read_b128 v[70:73], v95 offset:3072
	v_pk_mul_f32 v[74:75], v[82:83], v[94:95] op_sel_hi:[1,0]
	v_pk_mul_f32 v[76:77], v[84:85], v[94:95] op_sel_hi:[1,0]
	v_fmac_f32_e32 v37, v32, v32
	v_fmac_f32_e32 v43, v28, v28
	s_waitcnt lgkmcnt(0)
	v_pk_fma_f32 v[20:21], v[72:73], v[76:77], v[20:21]
	v_pk_fma_f32 v[18:19], v[70:71], v[74:75], v[18:19]
	ds_read_b128 v[70:73], v95 offset:4096
	v_mov_b32_e32 v74, v64
	v_mov_b32_e32 v75, v62
	v_mov_b32_e32 v76, v68
	v_mov_b32_e32 v77, v66
	v_pk_mul_f32 v[74:75], v[74:75], v[94:95] op_sel_hi:[1,0]
	v_pk_mul_f32 v[76:77], v[76:77], v[94:95] op_sel_hi:[1,0]
	s_waitcnt lgkmcnt(0)
	v_pk_fma_f32 v[14:15], v[70:71], v[74:75], v[14:15]
	v_pk_fma_f32 v[16:17], v[72:73], v[76:77], v[16:17]
	ds_read_b128 v[70:73], v95 offset:5120
	v_mov_b32_e32 v62, v65
	v_mov_b32_e32 v66, v69
	v_pk_mul_f32 v[62:63], v[62:63], v[94:95] op_sel_hi:[1,0]
	v_pk_mul_f32 v[64:65], v[66:67], v[94:95] op_sel_hi:[1,0]
	s_waitcnt lgkmcnt(0)
	v_pk_fma_f32 v[10:11], v[70:71], v[62:63], v[10:11]
	v_pk_fma_f32 v[12:13], v[72:73], v[64:65], v[12:13]
	ds_read_b128 v[62:65], v95 offset:6144
	v_mov_b32_e32 v66, v86
	v_mov_b32_e32 v67, v88
	v_mov_b32_e32 v68, v90
	v_mov_b32_e32 v69, v92
	v_pk_mul_f32 v[66:67], v[66:67], v[94:95] op_sel_hi:[1,0]
	v_pk_mul_f32 v[68:69], v[68:69], v[94:95] op_sel_hi:[1,0]
	s_waitcnt lgkmcnt(0)
	v_pk_fma_f32 v[6:7], v[62:63], v[66:67], v[6:7]
	v_pk_fma_f32 v[8:9], v[64:65], v[68:69], v[8:9]
	ds_read_b128 v[62:65], v95 offset:7168
	v_fmac_f32_e32 v37, v33, v33
	v_fmac_f32_e32 v43, v29, v29
	v_add_f32_e32 v37, v37, v43
	v_mul_f32_e32 v43, v23, v23
	v_fmac_f32_e32 v43, v22, v22
	v_mov_b32_e32 v88, v87
	v_mov_b32_e32 v92, v91
	v_fmac_f32_e32 v43, v24, v24
	v_pk_mul_f32 v[66:67], v[88:89], v[94:95] op_sel_hi:[1,0]
	v_pk_mul_f32 v[68:69], v[92:93], v[94:95] op_sel_hi:[1,0]
	v_fmac_f32_e32 v43, v25, v25
	s_waitcnt lgkmcnt(0)
	v_pk_fma_f32 v[4:5], v[64:65], v[68:69], v[4:5]
	v_pk_fma_f32 v[2:3], v[62:63], v[66:67], v[2:3]
	global_store_dwordx4 v[52:53], v[30:33], off nt
	global_store_dwordx4 v[52:53], v[26:29], off offset:1024 nt
	global_store_dwordx4 v[52:53], v[22:25], off offset:2048 nt
	global_store_dwordx4 v[52:53], v[18:21], off offset:3072 nt
	global_store_dwordx4 v[54:55], v[14:17], off nt
	global_store_dwordx4 v[56:57], v[10:13], off nt
	global_store_dwordx4 v[58:59], v[6:9], off nt
	global_store_dwordx4 v[60:61], v[2:5], off nt
	v_add_f32_e32 v37, v43, v37
	v_mul_f32_e32 v43, v19, v19
	v_mov_b32_e32 v54, v11
	v_mov_b32_e32 v55, v15
	v_fmac_f32_e32 v43, v18, v18
	v_mov_b32_e32 v52, v10
	v_mov_b32_e32 v53, v14
	v_pk_mul_f32 v[54:55], v[54:55], v[54:55]
	v_fmac_f32_e32 v43, v20, v20
	v_pk_fma_f32 v[52:53], v[52:53], v[52:53], v[54:55]
	v_mov_b32_e32 v54, v12
	v_mov_b32_e32 v55, v16
	v_fmac_f32_e32 v43, v21, v21
	v_pk_fma_f32 v[52:53], v[54:55], v[54:55], v[52:53]
	v_mov_b32_e32 v54, v13
	v_mov_b32_e32 v55, v17
	v_add_f32_e32 v37, v43, v37
	v_pk_fma_f32 v[52:53], v[54:55], v[54:55], v[52:53]
	v_mov_b32_e32 v54, v3
	v_add_f32_e32 v37, v53, v37
	v_mov_b32_e32 v55, v7
	v_add_f32_e32 v37, v52, v37
	v_mov_b32_e32 v52, v2
	v_mov_b32_e32 v53, v6
	v_pk_mul_f32 v[54:55], v[54:55], v[54:55]
	s_nop 0
	v_pk_fma_f32 v[52:53], v[52:53], v[52:53], v[54:55]
	v_mov_b32_e32 v54, v4
	v_mov_b32_e32 v55, v8
	v_pk_fma_f32 v[52:53], v[54:55], v[54:55], v[52:53]
	v_mov_b32_e32 v54, v5
	v_mov_b32_e32 v55, v9
	v_pk_fma_f32 v[52:53], v[54:55], v[54:55], v[52:53]
	ds_read_b128 v[54:57], v95 offset:8192
	ds_read_b128 v[58:61], v95 offset:16384
	v_add_f32_e32 v37, v53, v37
	v_add_f32_e32 v37, v52, v37
	v_mov_b32_e32 v120, v37
	v_mov_b32_e32 v121, v37
	s_nop 1
	v_permlane32_swap_b32_e32 v120, v121
	s_waitcnt lgkmcnt(0)
	v_add_f32_e32 v37, v120, v121
	v_mov_b32_e32 v120, v37
	v_mov_b32_e32 v121, v37
	s_nop 1
	v_permlane16_swap_b32_e32 v120, v121
	s_waitcnt lgkmcnt(0)
	v_add_f32_e32 v37, v120, v121
	s_nop 1
	s_waitcnt lgkmcnt(0)
	v_add_f32_dpp v37, v37, v37 row_ror:8 row_mask:0xf bank_mask:0xf
	s_nop 1
	v_mov_b32_dpp v120, v37 row_ror:4 row_mask:0xf bank_mask:0xa
	v_mov_b32_dpp v120, v37 row_ror:12 row_mask:0xf bank_mask:0x5
	s_waitcnt lgkmcnt(0)
; DI unsigned pack2(float lo, float hi) { f32x2 v = {lo, hi}; bf2_t b = __builtin_convertvector(v, bf2_t); return __builtin_bit_cast(unsigned, b); }
; DI float wave_sum(float v) { v += __shfl_xor(v, 32); v += __shfl_xor(v, 16); v += __shfl_xor(v, 8); v += __shfl_xor(v, 4); v += __shfl_xor(v, 2); v += __shfl_xor(v, 1); return v; }
; DI void rownorm_phase(const Params& P, const float* xin, const bf16_t* yin, float* xout, bf16_t* hout, int lg, int gate_idx, const float* w_post,
;                       int lh, int scale_idx, int shift_idx, const float* w_pre, char* smem) {
;     ...
;       ss = wave_sum(ss); const float r = rsqrtf(ss * (1.f / 2048.f) + EPS);
; #pragma unroll
;       for (int j = 0; j < 8; ++j) { const f32x4 a = *(const f32x4*)(A2 + (j * 64 + lane) * 4), b = *(const f32x4*)(B2 + (j * 64 + lane) * 4);
;         const f32x4 hv = xv[j] * r * a + b; u32x2 pk = {pack2(hv.x, hv.y), pack2(hv.z, hv.w)};
;         *(u32x2*)(hout + (size_t)row * 2048 + (j * 64 + lane) * 4) = pk; }
	v_add_f32_e32 v37, v37, v120
	s_nop 1
	s_waitcnt lgkmcnt(0)
	v_add_f32_dpp v37, v37, v37 quad_perm:[2,3,0,1] row_mask:0xf bank_mask:0xf
	s_nop 1
	s_waitcnt lgkmcnt(0)
	v_add_f32_dpp v37, v37, v37 quad_perm:[1,0,3,2] row_mask:0xf bank_mask:0xf
	v_fmamk_f32 v37, v37, 0x3a000000, v245
	v_cmp_gt_f32_e32 vcc, s84, v37
	v_mul_f32_e32 v43, 0x4b800000, v37
	s_nop 0
	v_cndmask_b32_e32 v37, v37, v43, vcc
	v_rsq_f32_e32 v37, v37
	s_nop 0
	v_mul_f32_e32 v43, 0x45800000, v37
	v_cndmask_b32_e32 v52, v37, v43, vcc
	v_pk_mul_f32 v[30:31], v[30:31], v[52:53] op_sel_hi:[1,0]
	v_pk_mul_f32 v[32:33], v[32:33], v[52:53] op_sel_hi:[1,0]
	v_pk_fma_f32 v[30:31], v[54:55], v[30:31], v[58:59]
	v_pk_fma_f32 v[32:33], v[56:57], v[32:33], v[60:61]
	v_cvt_pk_bf16_f32 v54, v30, v31
	v_cvt_pk_bf16_f32 v55, v32, v33
	v_lshl_add_u64 v[30:31], v[40:41], 0, v[50:51]
	global_store_dwordx2 v[30:31], v[54:55], off
	ds_read_b128 v[54:57], v95 offset:9216
	ds_read_b128 v[58:61], v95 offset:17408
	v_pk_mul_f32 v[26:27], v[26:27], v[52:53] op_sel_hi:[1,0]
	v_pk_mul_f32 v[28:29], v[28:29], v[52:53] op_sel_hi:[1,0]
	v_pk_mul_f32 v[22:23], v[22:23], v[52:53] op_sel_hi:[1,0]
	v_pk_mul_f32 v[24:25], v[24:25], v[52:53] op_sel_hi:[1,0]
	s_waitcnt lgkmcnt(0)
	v_pk_fma_f32 v[28:29], v[56:57], v[28:29], v[60:61]
	v_pk_fma_f32 v[26:27], v[54:55], v[26:27], v[58:59]
	v_pk_mul_f32 v[18:19], v[18:19], v[52:53] op_sel_hi:[1,0]
	v_cvt_pk_bf16_f32 v26, v26, v27
	v_cvt_pk_bf16_f32 v27, v28, v29
	global_store_dwordx2 v[30:31], v[26:27], off offset:512
	ds_read_b128 v[26:29], v95 offset:10240
	ds_read_b128 v[54:57], v95 offset:18432
	v_pk_mul_f32 v[20:21], v[20:21], v[52:53] op_sel_hi:[1,0]
	v_pk_mul_f32 v[14:15], v[14:15], v[52:53] op_sel_hi:[1,0]
	v_pk_mul_f32 v[16:17], v[16:17], v[52:53] op_sel_hi:[1,0]
	v_pk_mul_f32 v[10:11], v[10:11], v[52:53] op_sel_hi:[1,0]
	s_waitcnt lgkmcnt(0)
	v_pk_fma_f32 v[24:25], v[28:29], v[24:25], v[56:57]
	v_pk_fma_f32 v[22:23], v[26:27], v[22:23], v[54:55]
	v_pk_mul_f32 v[12:13], v[12:13], v[52:53] op_sel_hi:[1,0]
	v_cvt_pk_bf16_f32 v22, v22, v23
	v_cvt_pk_bf16_f32 v23, v24, v25
	global_store_dwordx2 v[30:31], v[22:23], off offset:1024
	ds_read_b128 v[22:25], v95 offset:11264
	ds_read_b128 v[26:29], v95 offset:19456
	v_pk_mul_f32 v[6:7], v[6:7], v[52:53] op_sel_hi:[1,0]
	v_pk_mul_f32 v[8:9], v[8:9], v[52:53] op_sel_hi:[1,0]
	v_pk_mul_f32 v[2:3], v[2:3], v[52:53] op_sel_hi:[1,0]
	v_pk_mul_f32 v[4:5], v[4:5], v[52:53] op_sel_hi:[1,0]
	s_waitcnt lgkmcnt(0)
	v_pk_fma_f32 v[20:21], v[24:25], v[20:21], v[28:29]
	v_pk_fma_f32 v[18:19], v[22:23], v[18:19], v[26:27]
	v_cmp_lt_i32_e32 vcc, s10, v36
	v_cvt_pk_bf16_f32 v18, v18, v19
	v_cvt_pk_bf16_f32 v19, v20, v21
	global_store_dwordx2 v[30:31], v[18:19], off offset:1536
	ds_read_b128 v[18:21], v95 offset:12288
	ds_read_b128 v[22:25], v95 offset:20480
	s_or_b64 s[8:9], vcc, s[8:9]
	s_waitcnt lgkmcnt(0)
	v_pk_fma_f32 v[16:17], v[20:21], v[16:17], v[24:25]
	v_pk_fma_f32 v[14:15], v[18:19], v[14:15], v[22:23]
	s_nop 0
	v_cvt_pk_bf16_f32 v14, v14, v15
	v_cvt_pk_bf16_f32 v15, v16, v17
	global_store_dwordx2 v[30:31], v[14:15], off offset:2048
	ds_read_b128 v[14:17], v95 offset:13312
	ds_read_b128 v[18:21], v95 offset:21504
	s_waitcnt lgkmcnt(0)
	v_pk_fma_f32 v[12:13], v[16:17], v[12:13], v[20:21]
	v_pk_fma_f32 v[10:11], v[14:15], v[10:11], v[18:19]
	s_nop 0
	v_cvt_pk_bf16_f32 v10, v10, v11
	v_cvt_pk_bf16_f32 v11, v12, v13
	global_store_dwordx2 v[30:31], v[10:11], off offset:2560
	ds_read_b128 v[10:13], v95 offset:14336
	ds_read_b128 v[14:17], v95 offset:22528
	s_waitcnt lgkmcnt(0)
	v_pk_fma_f32 v[8:9], v[12:13], v[8:9], v[16:17]
	v_pk_fma_f32 v[6:7], v[10:11], v[6:7], v[14:15]
	s_nop 0
	v_cvt_pk_bf16_f32 v6, v6, v7
	v_cvt_pk_bf16_f32 v7, v8, v9
	global_store_dwordx2 v[30:31], v[6:7], off offset:3072
	ds_read_b128 v[6:9], v95 offset:15360
	ds_read_b128 v[10:13], v95 offset:23552
	s_waitcnt lgkmcnt(0)
	v_pk_fma_f32 v[4:5], v[8:9], v[4:5], v[12:13]
	v_pk_fma_f32 v[2:3], v[6:7], v[2:3], v[10:11]
	s_nop 0
	v_cvt_pk_bf16_f32 v2, v2, v3
	v_cvt_pk_bf16_f32 v3, v4, v5
	global_store_dwordx2 v[30:31], v[2:3], off offset:3584
	s_andn2_b64 exec, exec, s[8:9]
	s_cbranch_execnz .LBB0_889

; DI float bflo(unsigned u) { return __uint_as_float(u << 16); }
; DI float bfhi(unsigned u) { return __uint_as_float(u & 0xffff0000u); }
; DI float wave_sum(float v) { v += __shfl_xor(v, 32); v += __shfl_xor(v, 16); v += __shfl_xor(v, 8); v += __shfl_xor(v, 4); v += __shfl_xor(v, 2); v += __shfl_xor(v, 1); return v; }
; DI void rownorm_phase(const Params& P, const float* xin, const bf16_t* yin, float* xout, bf16_t* hout, int lg, int gate_idx, const float* w_post,
;                       int lh, int scale_idx, int shift_idx, const float* w_pre, char* smem) {
;     ...
;     f32x4 xv[8];
; #pragma unroll
;     for (int j = 0; j < 8; ++j) xv[j] = __builtin_nontemporal_load((const f32x4*)(xin + (size_t)row * 2048 + (j * 64 + lane) * 4));
;     if (yin) {
;       f32x4 yv[8]; float ss = 0.f;
; #pragma unroll
;       for (int j = 0; j < 8; ++j) { const u32x2 yb = __builtin_nontemporal_load((const u32x2*)(yin + (size_t)row * 2048 + (j * 64 + lane) * 4)); yv[j] = (f32x4){bflo(yb.x), bfhi(yb.x), bflo(yb.y), bfhi(yb.y)};
;         ss += yv[j].x * yv[j].x + yv[j].y * yv[j].y + yv[j].z * yv[j].z + yv[j].w * yv[j].w; }
;       ss = wave_sum(ss); const float r = rsqrtf(ss * (1.f / 2048.f) + EPS);
.LBB0_1157:
	v_ashrrev_i32_e32 v37, 31, v36
	v_lshlrev_b64 v[2:3], 13, v[36:37]
	v_lshl_add_u64 v[2:3], v[34:35], 0, v[2:3]
	v_lshlrev_b64 v[58:59], 12, v[36:37]
	v_lshl_add_u64 v[54:55], v[2:3], 0, v[0:1]
	v_lshl_add_u64 v[82:83], v[38:39], 0, v[58:59]
	global_load_dwordx4 v[30:33], v[54:55], off nt
	global_load_dwordx4 v[26:29], v[54:55], off offset:1024 nt
	global_load_dwordx4 v[22:25], v[54:55], off offset:2048 nt
	global_load_dwordx4 v[18:21], v[54:55], off offset:3072 nt
	global_load_dwordx2 v[58:59], v[82:83], off nt
	v_mov_b32_e32 v41, v1
	v_mov_b32_e32 v43, v1
	v_mov_b32_e32 v45, v1
	v_mov_b32_e32 v47, v1
	v_lshl_add_u64 v[56:57], v[2:3], 0, v[40:41]
	v_lshl_add_u64 v[50:51], v[2:3], 0, v[42:43]
	v_lshl_add_u64 v[48:49], v[2:3], 0, v[44:45]
	v_lshl_add_u64 v[52:53], v[2:3], 0, v[46:47]
	global_load_dwordx4 v[14:17], v[56:57], off nt
	global_load_dwordx4 v[2:5], v[52:53], off nt
	global_load_dwordx4 v[10:13], v[50:51], off nt
	global_load_dwordx4 v[6:9], v[48:49], off nt
	v_add_u32_e32 v36, s79, v36
	global_load_dwordx2 v[106:107], v[82:83], off offset:512 nt
	global_load_dwordx2 v[108:109], v[82:83], off offset:1024 nt
	global_load_dwordx2 v[110:111], v[82:83], off offset:1536 nt
	global_load_dwordx2 v[84:85], v[82:83], off offset:2048 nt
	global_load_dwordx2 v[62:63], v[82:83], off offset:2560 nt
	global_load_dwordx2 v[98:99], v[82:83], off offset:3072 nt
	global_load_dwordx2 v[88:89], v[82:83], off offset:3584 nt
	s_waitcnt vmcnt(11)
	v_lshlrev_b32_e32 v66, 16, v58
	v_and_b32_e32 v67, 0xffff0000, v58
	v_lshlrev_b32_e32 v68, 16, v59
	v_and_b32_e32 v69, 0xffff0000, v59
	v_mul_f32_e32 v37, v67, v67
	v_fmac_f32_e32 v37, v66, v66
	v_fmac_f32_e32 v37, v68, v68
	v_fmac_f32_e32 v37, v69, v69
	s_waitcnt vmcnt(6)
	v_lshlrev_b32_e32 v70, 16, v106
	v_and_b32_e32 v71, 0xffff0000, v106
	v_lshlrev_b32_e32 v72, 16, v107
	v_and_b32_e32 v73, 0xffff0000, v107
	v_mul_f32_e32 v41, v71, v71
	v_fmac_f32_e32 v41, v70, v70
	v_fmac_f32_e32 v41, v72, v72
	v_fmac_f32_e32 v41, v73, v73
	v_add_f32_e32 v37, v37, v41
	s_waitcnt vmcnt(5)
	v_lshlrev_b32_e32 v74, 16, v108
	v_and_b32_e32 v75, 0xffff0000, v108
	v_lshlrev_b32_e32 v76, 16, v109
	v_and_b32_e32 v77, 0xffff0000, v109
	v_mul_f32_e32 v41, v75, v75
	v_fmac_f32_e32 v41, v74, v74
	v_fmac_f32_e32 v41, v76, v76
	v_fmac_f32_e32 v41, v77, v77
	v_add_f32_e32 v37, v37, v41
	s_waitcnt vmcnt(0)
	v_lshlrev_b32_e32 v60, 16, v84
	v_and_b32_e32 v79, 0xffff0000, v110
	v_lshlrev_b32_e32 v78, 16, v110
	v_lshlrev_b32_e32 v80, 16, v111
	v_and_b32_e32 v81, 0xffff0000, v111
	v_mul_f32_e32 v41, v79, v79
	v_and_b32_e32 v59, 0xffff0000, v62
	v_and_b32_e32 v58, 0xffff0000, v84
	v_fmac_f32_e32 v41, v78, v78
	v_lshlrev_b32_e32 v61, 16, v62
	v_lshlrev_b32_e32 v64, 16, v85
	v_and_b32_e32 v62, 0xffff0000, v85
	v_pk_mul_f32 v[84:85], v[58:59], v[58:59]
	v_fmac_f32_e32 v41, v80, v80
	v_lshlrev_b32_e32 v65, 16, v63
	v_pk_fma_f32 v[84:85], v[60:61], v[60:61], v[84:85]
	v_fmac_f32_e32 v41, v81, v81
	v_and_b32_e32 v63, 0xffff0000, v63
	v_pk_fma_f32 v[84:85], v[64:65], v[64:65], v[84:85]
	v_add_f32_e32 v37, v37, v41
	v_pk_fma_f32 v[84:85], v[62:63], v[62:63], v[84:85]
	v_lshlrev_b32_e32 v83, 16, v88
	v_add_f32_e32 v37, v37, v84
	v_add_f32_e32 v37, v37, v85
	v_and_b32_e32 v85, 0xffff0000, v88
	v_and_b32_e32 v84, 0xffff0000, v98
	v_lshlrev_b32_e32 v82, 16, v98
	v_lshlrev_b32_e32 v86, 16, v99
	v_and_b32_e32 v88, 0xffff0000, v99
	v_pk_mul_f32 v[98:99], v[84:85], v[84:85]
	v_lshlrev_b32_e32 v87, 16, v89
	v_pk_fma_f32 v[98:99], v[82:83], v[82:83], v[98:99]
	v_and_b32_e32 v89, 0xffff0000, v89
	v_pk_fma_f32 v[98:99], v[86:87], v[86:87], v[98:99]
	s_nop 0
	v_pk_fma_f32 v[98:99], v[88:89], v[88:89], v[98:99]
	s_nop 0
	v_add_f32_e32 v37, v37, v98
	v_add_f32_e32 v37, v37, v99
	v_mov_b32_e32 v120, v37
	v_mov_b32_e32 v121, v37
	s_nop 1
	v_permlane32_swap_b32_e32 v120, v121
	ds_read_b128 v[98:101], v91
	s_waitcnt lgkmcnt(0)
; DI float wave_sum(float v) { v += __shfl_xor(v, 32); v += __shfl_xor(v, 16); v += __shfl_xor(v, 8); v += __shfl_xor(v, 4); v += __shfl_xor(v, 2); v += __shfl_xor(v, 1); return v; }
; DI void rownorm_phase(const Params& P, const float* xin, const bf16_t* yin, float* xout, bf16_t* hout, int lg, int gate_idx, const float* w_post,
;                       int lh, int scale_idx, int shift_idx, const float* w_pre, char* smem) {
;     ...
;       ss = wave_sum(ss); const float r = rsqrtf(ss * (1.f / 2048.f) + EPS);
; #pragma unroll
;       for (int j = 0; j < 8; ++j) { const f32x4 a = *(const f32x4*)(A1 + (j * 64 + lane) * 4); xv[j] += a * (yv[j] * r); }
;     }
;     if (yin || xout != xin) {
; #pragma unroll
;       for (int j = 0; j < 8; ++j) __builtin_nontemporal_store(xv[j], (f32x4*)(xout + (size_t)row * 2048 + (j * 64 + lane) * 4));
	v_add_f32_e32 v37, v120, v121
	v_mov_b32_e32 v120, v37
	v_mov_b32_e32 v121, v37
	s_nop 1
	v_permlane16_swap_b32_e32 v120, v121
	s_waitcnt lgkmcnt(0)
	v_add_f32_e32 v37, v120, v121
	s_nop 1
	s_waitcnt lgkmcnt(0)
	v_add_f32_dpp v37, v37, v37 row_ror:8 row_mask:0xf bank_mask:0xf
	s_nop 1
	v_mov_b32_dpp v120, v37 row_ror:4 row_mask:0xf bank_mask:0xa
	v_mov_b32_dpp v120, v37 row_ror:12 row_mask:0xf bank_mask:0x5
	s_waitcnt lgkmcnt(0)
	v_add_f32_e32 v37, v37, v120
	s_nop 1
	s_waitcnt lgkmcnt(0)
	v_add_f32_dpp v37, v37, v37 quad_perm:[2,3,0,1] row_mask:0xf bank_mask:0xf
	s_nop 1
	s_waitcnt lgkmcnt(0)
	v_add_f32_dpp v37, v37, v37 quad_perm:[1,0,3,2] row_mask:0xf bank_mask:0xf
	v_fmamk_f32 v37, v37, 0x3a000000, v245
	v_cmp_gt_f32_e32 vcc, s84, v37
	v_mul_f32_e32 v41, 0x4b800000, v37
	s_nop 0
	v_cndmask_b32_e32 v37, v37, v41, vcc
	v_rsq_f32_e32 v37, v37
	s_nop 0
	v_mul_f32_e32 v41, 0x45800000, v37
	v_cndmask_b32_e32 v90, v37, v41, vcc
	v_pk_mul_f32 v[66:67], v[66:67], v[90:91] op_sel_hi:[1,0]
	v_pk_mul_f32 v[68:69], v[68:69], v[90:91] op_sel_hi:[1,0]
	v_pk_fma_f32 v[30:31], v[98:99], v[66:67], v[30:31]
	v_pk_fma_f32 v[32:33], v[100:101], v[68:69], v[32:33]
	ds_read_b128 v[66:69], v91 offset:1024
	v_pk_mul_f32 v[70:71], v[70:71], v[90:91] op_sel_hi:[1,0]
	v_pk_mul_f32 v[72:73], v[72:73], v[90:91] op_sel_hi:[1,0]
	v_cmp_lt_i32_e32 vcc, s4, v36
	s_or_b64 s[2:3], vcc, s[2:3]
	s_waitcnt lgkmcnt(0)
	v_pk_fma_f32 v[28:29], v[68:69], v[72:73], v[28:29]
	v_pk_fma_f32 v[26:27], v[66:67], v[70:71], v[26:27]
	ds_read_b128 v[66:69], v91 offset:2048
	v_pk_mul_f32 v[70:71], v[74:75], v[90:91] op_sel_hi:[1,0]
	v_pk_mul_f32 v[72:73], v[76:77], v[90:91] op_sel_hi:[1,0]
	s_waitcnt lgkmcnt(0)
	v_pk_fma_f32 v[22:23], v[66:67], v[70:71], v[22:23]
	v_pk_fma_f32 v[24:25], v[68:69], v[72:73], v[24:25]
	ds_read_b128 v[66:69], v91 offset:3072
	v_pk_mul_f32 v[70:71], v[78:79], v[90:91] op_sel_hi:[1,0]
	v_pk_mul_f32 v[72:73], v[80:81], v[90:91] op_sel_hi:[1,0]
	s_waitcnt lgkmcnt(0)
	v_pk_fma_f32 v[18:19], v[66:67], v[70:71], v[18:19]
	v_pk_fma_f32 v[20:21], v[68:69], v[72:73], v[20:21]
	ds_read_b128 v[66:69], v91 offset:4096
	v_mov_b32_e32 v70, v60
	v_mov_b32_e32 v71, v58
	v_mov_b32_e32 v72, v64
	v_mov_b32_e32 v73, v62
	v_pk_mul_f32 v[70:71], v[70:71], v[90:91] op_sel_hi:[1,0]
	v_pk_mul_f32 v[72:73], v[72:73], v[90:91] op_sel_hi:[1,0]
	s_waitcnt lgkmcnt(0)
	v_pk_fma_f32 v[14:15], v[66:67], v[70:71], v[14:15]
	v_pk_fma_f32 v[16:17], v[68:69], v[72:73], v[16:17]
	ds_read_b128 v[66:69], v91 offset:5120
	v_mov_b32_e32 v58, v61
	v_mov_b32_e32 v62, v65
	v_pk_mul_f32 v[58:59], v[58:59], v[90:91] op_sel_hi:[1,0]
	v_pk_mul_f32 v[60:61], v[62:63], v[90:91] op_sel_hi:[1,0]
	s_waitcnt lgkmcnt(0)
	v_pk_fma_f32 v[10:11], v[66:67], v[58:59], v[10:11]
	v_pk_fma_f32 v[12:13], v[68:69], v[60:61], v[12:13]
	ds_read_b128 v[58:61], v91 offset:6144
	v_mov_b32_e32 v62, v82
	v_mov_b32_e32 v63, v84
	v_mov_b32_e32 v64, v86
	v_mov_b32_e32 v65, v88
	v_pk_mul_f32 v[62:63], v[62:63], v[90:91] op_sel_hi:[1,0]
	v_pk_mul_f32 v[64:65], v[64:65], v[90:91] op_sel_hi:[1,0]
	s_waitcnt lgkmcnt(0)
	v_pk_fma_f32 v[6:7], v[58:59], v[62:63], v[6:7]
	v_pk_fma_f32 v[8:9], v[60:61], v[64:65], v[8:9]
	ds_read_b128 v[58:61], v91 offset:7168
	v_mov_b32_e32 v84, v83
	v_mov_b32_e32 v88, v87
	v_pk_mul_f32 v[62:63], v[84:85], v[90:91] op_sel_hi:[1,0]
	v_pk_mul_f32 v[64:65], v[88:89], v[90:91] op_sel_hi:[1,0]
	s_waitcnt lgkmcnt(0)
	v_pk_fma_f32 v[2:3], v[58:59], v[62:63], v[2:3]
	v_pk_fma_f32 v[4:5], v[60:61], v[64:65], v[4:5]
	global_store_dwordx4 v[54:55], v[30:33], off nt
	global_store_dwordx4 v[54:55], v[26:29], off offset:1024 nt
	global_store_dwordx4 v[54:55], v[22:25], off offset:2048 nt
	global_store_dwordx4 v[54:55], v[18:21], off offset:3072 nt
	global_store_dwordx4 v[56:57], v[14:17], off nt
	global_store_dwordx4 v[50:51], v[10:13], off nt
	global_store_dwordx4 v[48:49], v[6:9], off nt
	global_store_dwordx4 v[52:53], v[2:5], off nt
	s_andn2_b64 exec, exec, s[2:3]
	s_cbranch_execnz .LBB0_1157

; DI float bflo(unsigned u) { return __uint_as_float(u << 16); }
; DI float bfhi(unsigned u) { return __uint_as_float(u & 0xffff0000u); }
; DI float wave_sum(float v) { v += __shfl_xor(v, 32); v += __shfl_xor(v, 16); v += __shfl_xor(v, 8); v += __shfl_xor(v, 4); v += __shfl_xor(v, 2); v += __shfl_xor(v, 1); return v; }
; DI void rownorm_phase(const Params& P, const float* xin, const bf16_t* yin, float* xout, bf16_t* hout, int lg, int gate_idx, const float* w_post,
;                       int lh, int scale_idx, int shift_idx, const float* w_pre, char* smem) {
;     ...
;     f32x4 xv[8];
; #pragma unroll
;     for (int j = 0; j < 8; ++j) xv[j] = __builtin_nontemporal_load((const f32x4*)(xin + (size_t)row * 2048 + (j * 64 + lane) * 4));
;     if (yin) {
;       f32x4 yv[8]; float ss = 0.f;
; #pragma unroll
;       for (int j = 0; j < 8; ++j) { const u32x2 yb = __builtin_nontemporal_load((const u32x2*)(yin + (size_t)row * 2048 + (j * 64 + lane) * 4)); yv[j] = (f32x4){bflo(yb.x), bfhi(yb.x), bflo(yb.y), bfhi(yb.y)};
;         ss += yv[j].x * yv[j].x + yv[j].y * yv[j].y + yv[j].z * yv[j].z + yv[j].w * yv[j].w; }
;       ss = wave_sum(ss); const float r = rsqrtf(ss * (1.f / 2048.f) + EPS);
; #pragma unroll
;       for (int j = 0; j < 8; ++j) { const f32x4 a = *(const f32x4*)(A1 + (j * 64 + lane) * 4); xv[j] += a * (yv[j] * r); }
.LBB0_1236:
	v_ashrrev_i32_e32 v37, 31, v36
	v_lshlrev_b64 v[2:3], 13, v[36:37]
	v_lshl_add_u64 v[2:3], v[34:35], 0, v[2:3]
	v_lshlrev_b64 v[50:51], 12, v[36:37]
	v_lshl_add_u64 v[52:53], v[2:3], 0, v[0:1]
	v_lshl_add_u64 v[86:87], v[38:39], 0, v[50:51]
	global_load_dwordx4 v[30:33], v[52:53], off nt
	global_load_dwordx4 v[26:29], v[52:53], off offset:1024 nt
	global_load_dwordx4 v[22:25], v[52:53], off offset:2048 nt
	global_load_dwordx4 v[18:21], v[52:53], off offset:3072 nt
	global_load_dwordx2 v[62:63], v[86:87], off nt
	v_mov_b32_e32 v43, v1
	v_mov_b32_e32 v45, v1
	v_mov_b32_e32 v47, v1
	v_mov_b32_e32 v49, v1
	v_lshl_add_u64 v[54:55], v[2:3], 0, v[42:43]
	v_lshl_add_u64 v[56:57], v[2:3], 0, v[44:45]
	v_lshl_add_u64 v[58:59], v[2:3], 0, v[46:47]
	v_lshl_add_u64 v[60:61], v[2:3], 0, v[48:49]
	global_load_dwordx4 v[14:17], v[54:55], off nt
	global_load_dwordx4 v[10:13], v[56:57], off nt
	global_load_dwordx4 v[6:9], v[58:59], off nt
	global_load_dwordx4 v[2:5], v[60:61], off nt
	v_add_u32_e32 v36, s79, v36
	global_load_dwordx2 v[106:107], v[86:87], off offset:512 nt
	global_load_dwordx2 v[108:109], v[86:87], off offset:1024 nt
	global_load_dwordx2 v[110:111], v[86:87], off offset:1536 nt
	global_load_dwordx2 v[88:89], v[86:87], off offset:2048 nt
	global_load_dwordx2 v[66:67], v[86:87], off offset:2560 nt
	global_load_dwordx2 v[102:103], v[86:87], off offset:3072 nt
	global_load_dwordx2 v[92:93], v[86:87], off offset:3584 nt
	s_waitcnt vmcnt(11)
	v_lshlrev_b32_e32 v70, 16, v62
	v_and_b32_e32 v71, 0xffff0000, v62
	v_lshlrev_b32_e32 v72, 16, v63
	v_and_b32_e32 v73, 0xffff0000, v63
	v_mul_f32_e32 v37, v71, v71
	v_fmac_f32_e32 v37, v70, v70
	v_fmac_f32_e32 v37, v72, v72
	v_fmac_f32_e32 v37, v73, v73
	s_waitcnt vmcnt(6)
	v_lshlrev_b32_e32 v74, 16, v106
	v_and_b32_e32 v75, 0xffff0000, v106
	v_lshlrev_b32_e32 v76, 16, v107
	v_and_b32_e32 v77, 0xffff0000, v107
	v_mul_f32_e32 v43, v75, v75
	v_fmac_f32_e32 v43, v74, v74
	v_fmac_f32_e32 v43, v76, v76
	v_fmac_f32_e32 v43, v77, v77
	v_add_f32_e32 v37, v37, v43
	s_waitcnt vmcnt(5)
	v_lshlrev_b32_e32 v78, 16, v108
	v_and_b32_e32 v79, 0xffff0000, v108
	v_lshlrev_b32_e32 v80, 16, v109
	v_and_b32_e32 v81, 0xffff0000, v109
	v_mul_f32_e32 v43, v79, v79
	v_fmac_f32_e32 v43, v78, v78
	v_fmac_f32_e32 v43, v80, v80
	v_fmac_f32_e32 v43, v81, v81
	v_add_f32_e32 v37, v37, v43
	s_waitcnt vmcnt(0)
	v_lshlrev_b32_e32 v64, 16, v88
	v_and_b32_e32 v83, 0xffff0000, v110
	v_lshlrev_b32_e32 v82, 16, v110
	v_lshlrev_b32_e32 v84, 16, v111
	v_and_b32_e32 v85, 0xffff0000, v111
	v_mul_f32_e32 v43, v83, v83
	v_and_b32_e32 v63, 0xffff0000, v66
	v_and_b32_e32 v62, 0xffff0000, v88
	v_fmac_f32_e32 v43, v82, v82
	v_lshlrev_b32_e32 v65, 16, v66
	v_lshlrev_b32_e32 v68, 16, v89
	v_and_b32_e32 v66, 0xffff0000, v89
	v_pk_mul_f32 v[88:89], v[62:63], v[62:63]
	v_fmac_f32_e32 v43, v84, v84
	v_lshlrev_b32_e32 v69, 16, v67
	v_pk_fma_f32 v[88:89], v[64:65], v[64:65], v[88:89]
	v_fmac_f32_e32 v43, v85, v85
	v_and_b32_e32 v67, 0xffff0000, v67
	v_pk_fma_f32 v[88:89], v[68:69], v[68:69], v[88:89]
	v_add_f32_e32 v37, v37, v43
	v_pk_fma_f32 v[88:89], v[66:67], v[66:67], v[88:89]
	v_lshlrev_b32_e32 v87, 16, v92
	v_add_f32_e32 v37, v37, v88
	v_add_f32_e32 v37, v37, v89
	v_and_b32_e32 v89, 0xffff0000, v92
	v_and_b32_e32 v88, 0xffff0000, v102
	v_lshlrev_b32_e32 v86, 16, v102
	v_lshlrev_b32_e32 v90, 16, v103
	v_and_b32_e32 v92, 0xffff0000, v103
	v_pk_mul_f32 v[102:103], v[88:89], v[88:89]
	v_lshlrev_b32_e32 v91, 16, v93
	v_pk_fma_f32 v[102:103], v[86:87], v[86:87], v[102:103]
	v_and_b32_e32 v93, 0xffff0000, v93
	v_pk_fma_f32 v[102:103], v[90:91], v[90:91], v[102:103]
	s_nop 0
	v_pk_fma_f32 v[102:103], v[92:93], v[92:93], v[102:103]
	s_nop 0
	v_add_f32_e32 v37, v37, v102
	v_add_f32_e32 v37, v37, v103
	v_mov_b32_e32 v120, v37
	v_mov_b32_e32 v121, v37
	s_nop 1
	v_permlane32_swap_b32_e32 v120, v121
	ds_read_b128 v[102:105], v95
	s_waitcnt lgkmcnt(0)
	v_add_f32_e32 v37, v120, v121
	v_mov_b32_e32 v120, v37
	v_mov_b32_e32 v121, v37
	s_nop 1
	v_permlane16_swap_b32_e32 v120, v121
	s_waitcnt lgkmcnt(0)
	v_add_f32_e32 v37, v120, v121
	s_nop 1
	s_waitcnt lgkmcnt(0)
	v_add_f32_dpp v37, v37, v37 row_ror:8 row_mask:0xf bank_mask:0xf
	s_nop 1
	v_mov_b32_dpp v120, v37 row_ror:4 row_mask:0xf bank_mask:0xa
	v_mov_b32_dpp v120, v37 row_ror:12 row_mask:0xf bank_mask:0x5
	s_waitcnt lgkmcnt(0)
	v_add_f32_e32 v37, v37, v120
	s_nop 1
	s_waitcnt lgkmcnt(0)
	v_add_f32_dpp v37, v37, v37 quad_perm:[2,3,0,1] row_mask:0xf bank_mask:0xf
	s_nop 1
	s_waitcnt lgkmcnt(0)
	v_add_f32_dpp v37, v37, v37 quad_perm:[1,0,3,2] row_mask:0xf bank_mask:0xf
	v_fmamk_f32 v37, v37, 0x3a000000, v245
	v_cmp_gt_f32_e32 vcc, s84, v37
	v_mul_f32_e32 v43, 0x4b800000, v37
	s_nop 0
	v_cndmask_b32_e32 v37, v37, v43, vcc
	v_rsq_f32_e32 v37, v37
	s_nop 0
	v_mul_f32_e32 v43, 0x45800000, v37
	v_cndmask_b32_e32 v94, v37, v43, vcc
	v_pk_mul_f32 v[70:71], v[70:71], v[94:95] op_sel_hi:[1,0]
	v_pk_mul_f32 v[72:73], v[72:73], v[94:95] op_sel_hi:[1,0]
	v_pk_fma_f32 v[30:31], v[102:103], v[70:71], v[30:31]
	v_pk_fma_f32 v[32:33], v[104:105], v[72:73], v[32:33]
	ds_read_b128 v[70:73], v95 offset:1024
	v_pk_mul_f32 v[74:75], v[74:75], v[94:95] op_sel_hi:[1,0]
	v_pk_mul_f32 v[76:77], v[76:77], v[94:95] op_sel_hi:[1,0]
	v_mul_f32_e32 v37, v31, v31
	v_fmac_f32_e32 v37, v30, v30
	s_waitcnt lgkmcnt(0)
	v_pk_fma_f32 v[28:29], v[72:73], v[76:77], v[28:29]
	v_pk_fma_f32 v[26:27], v[70:71], v[74:75], v[26:27]
	ds_read_b128 v[70:73], v95 offset:2048
	v_pk_mul_f32 v[74:75], v[78:79], v[94:95] op_sel_hi:[1,0]
	v_pk_mul_f32 v[76:77], v[80:81], v[94:95] op_sel_hi:[1,0]
	v_mul_f32_e32 v43, v27, v27
	v_fmac_f32_e32 v43, v26, v26
	s_waitcnt lgkmcnt(0)
; DI float wave_sum(float v) { v += __shfl_xor(v, 32); v += __shfl_xor(v, 16); v += __shfl_xor(v, 8); v += __shfl_xor(v, 4); v += __shfl_xor(v, 2); v += __shfl_xor(v, 1); return v; }
; DI void rownorm_phase(const Params& P, const float* xin, const bf16_t* yin, float* xout, bf16_t* hout, int lg, int gate_idx, const float* w_post,
;                       int lh, int scale_idx, int shift_idx, const float* w_pre, char* smem) {
;     ...
;       for (int j = 0; j < 8; ++j) { const f32x4 a = *(const f32x4*)(A1 + (j * 64 + lane) * 4); xv[j] += a * (yv[j] * r); }
;     }
;     if (yin || xout != xin) {
; #pragma unroll
;       for (int j = 0; j < 8; ++j) __builtin_nontemporal_store(xv[j], (f32x4*)(xout + (size_t)row * 2048 + (j * 64 + lane) * 4));
;     }
;     if (hout) {
;       float ss = 0.f;
; #pragma unroll
;       for (int j = 0; j < 8; ++j) ss += xv[j].x * xv[j].x + xv[j].y * xv[j].y + xv[j].z * xv[j].z + xv[j].w * xv[j].w;
;       ss = wave_sum(ss); const float r = rsqrtf(ss * (1.f / 2048.f) + EPS);
	v_pk_fma_f32 v[24:25], v[72:73], v[76:77], v[24:25]
	v_pk_fma_f32 v[22:23], v[70:71], v[74:75], v[22:23]
	ds_read_b128 v[70:73], v95 offset:3072
	v_pk_mul_f32 v[74:75], v[82:83], v[94:95] op_sel_hi:[1,0]
	v_pk_mul_f32 v[76:77], v[84:85], v[94:95] op_sel_hi:[1,0]
	v_fmac_f32_e32 v37, v32, v32
	v_fmac_f32_e32 v43, v28, v28
	s_waitcnt lgkmcnt(0)
	v_pk_fma_f32 v[20:21], v[72:73], v[76:77], v[20:21]
	v_pk_fma_f32 v[18:19], v[70:71], v[74:75], v[18:19]
	ds_read_b128 v[70:73], v95 offset:4096
	v_mov_b32_e32 v74, v64
	v_mov_b32_e32 v75, v62
	v_mov_b32_e32 v76, v68
	v_mov_b32_e32 v77, v66
	v_pk_mul_f32 v[74:75], v[74:75], v[94:95] op_sel_hi:[1,0]
	v_pk_mul_f32 v[76:77], v[76:77], v[94:95] op_sel_hi:[1,0]
	s_waitcnt lgkmcnt(0)
	v_pk_fma_f32 v[14:15], v[70:71], v[74:75], v[14:15]
	v_pk_fma_f32 v[16:17], v[72:73], v[76:77], v[16:17]
	ds_read_b128 v[70:73], v95 offset:5120
	v_mov_b32_e32 v62, v65
	v_mov_b32_e32 v66, v69
	v_pk_mul_f32 v[62:63], v[62:63], v[94:95] op_sel_hi:[1,0]
	v_pk_mul_f32 v[64:65], v[66:67], v[94:95] op_sel_hi:[1,0]
	s_waitcnt lgkmcnt(0)
	v_pk_fma_f32 v[10:11], v[70:71], v[62:63], v[10:11]
	v_pk_fma_f32 v[12:13], v[72:73], v[64:65], v[12:13]
	ds_read_b128 v[62:65], v95 offset:6144
	v_mov_b32_e32 v66, v86
	v_mov_b32_e32 v67, v88
	v_mov_b32_e32 v68, v90
	v_mov_b32_e32 v69, v92
	v_pk_mul_f32 v[66:67], v[66:67], v[94:95] op_sel_hi:[1,0]
	v_pk_mul_f32 v[68:69], v[68:69], v[94:95] op_sel_hi:[1,0]
	s_waitcnt lgkmcnt(0)
	v_pk_fma_f32 v[6:7], v[62:63], v[66:67], v[6:7]
	v_pk_fma_f32 v[8:9], v[64:65], v[68:69], v[8:9]
	ds_read_b128 v[62:65], v95 offset:7168
	v_fmac_f32_e32 v37, v33, v33
	v_fmac_f32_e32 v43, v29, v29
	v_add_f32_e32 v37, v37, v43
	v_mul_f32_e32 v43, v23, v23
	v_fmac_f32_e32 v43, v22, v22
	v_mov_b32_e32 v88, v87
	v_mov_b32_e32 v92, v91
	v_fmac_f32_e32 v43, v24, v24
	v_pk_mul_f32 v[66:67], v[88:89], v[94:95] op_sel_hi:[1,0]
	v_pk_mul_f32 v[68:69], v[92:93], v[94:95] op_sel_hi:[1,0]
	v_fmac_f32_e32 v43, v25, v25
	s_waitcnt lgkmcnt(0)
	v_pk_fma_f32 v[4:5], v[64:65], v[68:69], v[4:5]
	v_pk_fma_f32 v[2:3], v[62:63], v[66:67], v[2:3]
	global_store_dwordx4 v[52:53], v[30:33], off nt
	global_store_dwordx4 v[52:53], v[26:29], off offset:1024 nt
	global_store_dwordx4 v[52:53], v[22:25], off offset:2048 nt
	global_store_dwordx4 v[52:53], v[18:21], off offset:3072 nt
	global_store_dwordx4 v[54:55], v[14:17], off nt
	global_store_dwordx4 v[56:57], v[10:13], off nt
	global_store_dwordx4 v[58:59], v[6:9], off nt
	global_store_dwordx4 v[60:61], v[2:5], off nt
	v_add_f32_e32 v37, v43, v37
	v_mul_f32_e32 v43, v19, v19
	v_mov_b32_e32 v54, v11
	v_mov_b32_e32 v55, v15
	v_fmac_f32_e32 v43, v18, v18
	v_mov_b32_e32 v52, v10
	v_mov_b32_e32 v53, v14
	v_pk_mul_f32 v[54:55], v[54:55], v[54:55]
	v_fmac_f32_e32 v43, v20, v20
	v_pk_fma_f32 v[52:53], v[52:53], v[52:53], v[54:55]
	v_mov_b32_e32 v54, v12
	v_mov_b32_e32 v55, v16
	v_fmac_f32_e32 v43, v21, v21
	v_pk_fma_f32 v[52:53], v[54:55], v[54:55], v[52:53]
	v_mov_b32_e32 v54, v13
	v_mov_b32_e32 v55, v17
	v_add_f32_e32 v37, v43, v37
	v_pk_fma_f32 v[52:53], v[54:55], v[54:55], v[52:53]
	v_mov_b32_e32 v54, v3
	v_add_f32_e32 v37, v53, v37
	v_mov_b32_e32 v55, v7
	v_add_f32_e32 v37, v52, v37
	v_mov_b32_e32 v52, v2
	v_mov_b32_e32 v53, v6
	v_pk_mul_f32 v[54:55], v[54:55], v[54:55]
	s_nop 0
	v_pk_fma_f32 v[52:53], v[52:53], v[52:53], v[54:55]
	v_mov_b32_e32 v54, v4
	v_mov_b32_e32 v55, v8
	v_pk_fma_f32 v[52:53], v[54:55], v[54:55], v[52:53]
	v_mov_b32_e32 v54, v5
	v_mov_b32_e32 v55, v9
	v_pk_fma_f32 v[52:53], v[54:55], v[54:55], v[52:53]
	ds_read_b128 v[54:57], v95 offset:8192
	ds_read_b128 v[58:61], v95 offset:16384
	v_add_f32_e32 v37, v53, v37
	v_add_f32_e32 v37, v52, v37
	v_mov_b32_e32 v120, v37
	v_mov_b32_e32 v121, v37
	s_nop 1
	v_permlane32_swap_b32_e32 v120, v121
	s_waitcnt lgkmcnt(0)
	v_add_f32_e32 v37, v120, v121
	v_mov_b32_e32 v120, v37
	v_mov_b32_e32 v121, v37
	s_nop 1
	v_permlane16_swap_b32_e32 v120, v121
	s_waitcnt lgkmcnt(0)
	v_add_f32_e32 v37, v120, v121
	s_nop 1
	s_waitcnt lgkmcnt(0)
	v_add_f32_dpp v37, v37, v37 row_ror:8 row_mask:0xf bank_mask:0xf
	s_nop 1
	v_mov_b32_dpp v120, v37 row_ror:4 row_mask:0xf bank_mask:0xa
	v_mov_b32_dpp v120, v37 row_ror:12 row_mask:0xf bank_mask:0x5
	s_waitcnt lgkmcnt(0)
; DI unsigned pack2(float lo, float hi) { f32x2 v = {lo, hi}; bf2_t b = __builtin_convertvector(v, bf2_t); return __builtin_bit_cast(unsigned, b); }
; DI float wave_sum(float v) { v += __shfl_xor(v, 32); v += __shfl_xor(v, 16); v += __shfl_xor(v, 8); v += __shfl_xor(v, 4); v += __shfl_xor(v, 2); v += __shfl_xor(v, 1); return v; }
; DI void rownorm_phase(const Params& P, const float* xin, const bf16_t* yin, float* xout, bf16_t* hout, int lg, int gate_idx, const float* w_post,
;                       int lh, int scale_idx, int shift_idx, const float* w_pre, char* smem) {
;     ...
;       ss = wave_sum(ss); const float r = rsqrtf(ss * (1.f / 2048.f) + EPS);
; #pragma unroll
;       for (int j = 0; j < 8; ++j) { const f32x4 a = *(const f32x4*)(A2 + (j * 64 + lane) * 4), b = *(const f32x4*)(B2 + (j * 64 + lane) * 4);
;         const f32x4 hv = xv[j] * r * a + b; u32x2 pk = {pack2(hv.x, hv.y), pack2(hv.z, hv.w)};
;         *(u32x2*)(hout + (size_t)row * 2048 + (j * 64 + lane) * 4) = pk; }
	v_add_f32_e32 v37, v37, v120
	s_nop 1
	s_waitcnt lgkmcnt(0)
	v_add_f32_dpp v37, v37, v37 quad_perm:[2,3,0,1] row_mask:0xf bank_mask:0xf
	s_nop 1
	s_waitcnt lgkmcnt(0)
	v_add_f32_dpp v37, v37, v37 quad_perm:[1,0,3,2] row_mask:0xf bank_mask:0xf
	v_fmamk_f32 v37, v37, 0x3a000000, v245
	v_cmp_gt_f32_e32 vcc, s84, v37
	v_mul_f32_e32 v43, 0x4b800000, v37
	s_nop 0
	v_cndmask_b32_e32 v37, v37, v43, vcc
	v_rsq_f32_e32 v37, v37
	s_nop 0
	v_mul_f32_e32 v43, 0x45800000, v37
	v_cndmask_b32_e32 v52, v37, v43, vcc
	v_pk_mul_f32 v[30:31], v[30:31], v[52:53] op_sel_hi:[1,0]
	v_pk_mul_f32 v[32:33], v[32:33], v[52:53] op_sel_hi:[1,0]
	v_pk_fma_f32 v[30:31], v[54:55], v[30:31], v[58:59]
	v_pk_fma_f32 v[32:33], v[56:57], v[32:33], v[60:61]
	v_cvt_pk_bf16_f32 v54, v30, v31
	v_cvt_pk_bf16_f32 v55, v32, v33
	v_lshl_add_u64 v[30:31], v[40:41], 0, v[50:51]
	global_store_dwordx2 v[30:31], v[54:55], off
	ds_read_b128 v[54:57], v95 offset:9216
	ds_read_b128 v[58:61], v95 offset:17408
	v_pk_mul_f32 v[26:27], v[26:27], v[52:53] op_sel_hi:[1,0]
	v_pk_mul_f32 v[28:29], v[28:29], v[52:53] op_sel_hi:[1,0]
	v_pk_mul_f32 v[22:23], v[22:23], v[52:53] op_sel_hi:[1,0]
	v_pk_mul_f32 v[24:25], v[24:25], v[52:53] op_sel_hi:[1,0]
	s_waitcnt lgkmcnt(0)
	v_pk_fma_f32 v[28:29], v[56:57], v[28:29], v[60:61]
	v_pk_fma_f32 v[26:27], v[54:55], v[26:27], v[58:59]
	v_pk_mul_f32 v[18:19], v[18:19], v[52:53] op_sel_hi:[1,0]
	v_cvt_pk_bf16_f32 v26, v26, v27
	v_cvt_pk_bf16_f32 v27, v28, v29
	global_store_dwordx2 v[30:31], v[26:27], off offset:512
	ds_read_b128 v[26:29], v95 offset:10240
	ds_read_b128 v[54:57], v95 offset:18432
	v_pk_mul_f32 v[20:21], v[20:21], v[52:53] op_sel_hi:[1,0]
	v_pk_mul_f32 v[14:15], v[14:15], v[52:53] op_sel_hi:[1,0]
	v_pk_mul_f32 v[16:17], v[16:17], v[52:53] op_sel_hi:[1,0]
	v_pk_mul_f32 v[10:11], v[10:11], v[52:53] op_sel_hi:[1,0]
	s_waitcnt lgkmcnt(0)
	v_pk_fma_f32 v[24:25], v[28:29], v[24:25], v[56:57]
	v_pk_fma_f32 v[22:23], v[26:27], v[22:23], v[54:55]
	v_pk_mul_f32 v[12:13], v[12:13], v[52:53] op_sel_hi:[1,0]
	v_cvt_pk_bf16_f32 v22, v22, v23
	v_cvt_pk_bf16_f32 v23, v24, v25
	global_store_dwordx2 v[30:31], v[22:23], off offset:1024
	ds_read_b128 v[22:25], v95 offset:11264
	ds_read_b128 v[26:29], v95 offset:19456
	v_pk_mul_f32 v[6:7], v[6:7], v[52:53] op_sel_hi:[1,0]
	v_pk_mul_f32 v[8:9], v[8:9], v[52:53] op_sel_hi:[1,0]
	v_pk_mul_f32 v[2:3], v[2:3], v[52:53] op_sel_hi:[1,0]
	v_pk_mul_f32 v[4:5], v[4:5], v[52:53] op_sel_hi:[1,0]
	s_waitcnt lgkmcnt(0)
	v_pk_fma_f32 v[20:21], v[24:25], v[20:21], v[28:29]
	v_pk_fma_f32 v[18:19], v[22:23], v[18:19], v[26:27]
	v_cmp_lt_i32_e32 vcc, s4, v36
	v_cvt_pk_bf16_f32 v18, v18, v19
	v_cvt_pk_bf16_f32 v19, v20, v21
	global_store_dwordx2 v[30:31], v[18:19], off offset:1536
	ds_read_b128 v[18:21], v95 offset:12288
	ds_read_b128 v[22:25], v95 offset:20480
	s_or_b64 s[2:3], vcc, s[2:3]
	s_waitcnt lgkmcnt(0)
	v_pk_fma_f32 v[16:17], v[20:21], v[16:17], v[24:25]
	v_pk_fma_f32 v[14:15], v[18:19], v[14:15], v[22:23]
	s_nop 0
	v_cvt_pk_bf16_f32 v14, v14, v15
	v_cvt_pk_bf16_f32 v15, v16, v17
	global_store_dwordx2 v[30:31], v[14:15], off offset:2048
	ds_read_b128 v[14:17], v95 offset:13312
	ds_read_b128 v[18:21], v95 offset:21504
	s_waitcnt lgkmcnt(0)
	v_pk_fma_f32 v[12:13], v[16:17], v[12:13], v[20:21]
	v_pk_fma_f32 v[10:11], v[14:15], v[10:11], v[18:19]
	s_nop 0
	v_cvt_pk_bf16_f32 v10, v10, v11
	v_cvt_pk_bf16_f32 v11, v12, v13
	global_store_dwordx2 v[30:31], v[10:11], off offset:2560
	ds_read_b128 v[10:13], v95 offset:14336
	ds_read_b128 v[14:17], v95 offset:22528
	s_waitcnt lgkmcnt(0)
	v_pk_fma_f32 v[8:9], v[12:13], v[8:9], v[16:17]
	v_pk_fma_f32 v[6:7], v[10:11], v[6:7], v[14:15]
	s_nop 0
	v_cvt_pk_bf16_f32 v6, v6, v7
	v_cvt_pk_bf16_f32 v7, v8, v9
	global_store_dwordx2 v[30:31], v[6:7], off offset:3072
	ds_read_b128 v[6:9], v95 offset:15360
	ds_read_b128 v[10:13], v95 offset:23552
	s_waitcnt lgkmcnt(0)
	v_pk_fma_f32 v[4:5], v[8:9], v[4:5], v[12:13]
	v_pk_fma_f32 v[2:3], v[6:7], v[2:3], v[10:11]
	s_nop 0
	v_cvt_pk_bf16_f32 v2, v2, v3
	v_cvt_pk_bf16_f32 v3, v4, v5
	global_store_dwordx2 v[30:31], v[2:3], off offset:3584
	s_andn2_b64 exec, exec, s[2:3]
	s_cbranch_execnz .LBB0_1236
